# qkconv conv loop: wave-uniform row / halo / address arithmetic moved to SALU (saddr loads and stores), zero-padding taps skipped; on top of hoist + next-trip prefetch
# baseline (speedup 1.0000x reference)
.LBB0_1608:
	s_or_b64 exec, exec, s[18:19]
	v_lshl_add_u32 v2, s2, 9, v128
	s_mov_b32 s0, 0x240000
	v_cmp_gt_i32_e32 vcc, s0, v2
	s_and_saveexec_b64 s[6:7], vcc
	v_readlane_b32 s36, v252, 16
	v_readlane_b32 s50, v252, 30
	v_readlane_b32 s51, v252, 31
	v_readlane_b32 s37, v252, 17
	v_readlane_b32 s38, v252, 18
	v_readlane_b32 s39, v252, 19
	v_readlane_b32 s40, v252, 20
	v_readlane_b32 s41, v252, 21
	v_readlane_b32 s42, v252, 22
	v_readlane_b32 s43, v252, 23
	v_readlane_b32 s44, v252, 24
	v_readlane_b32 s45, v252, 25
	v_readlane_b32 s46, v252, 26
	v_readlane_b32 s47, v252, 27
	v_readlane_b32 s48, v252, 28
	v_readlane_b32 s49, v252, 29
	s_cbranch_execz .LBB0_1611
	v_lshlrev_b32_e32 v0, 3, v128
	s_mov_b64 s[26:27], s[50:51]
	s_lshl_b32 s14, s22, 9
	v_lshl_add_u32 v3, s2, 12, v0
	s_lshl_b32 s15, s22, 12
	s_mov_b64 s[8:9], 0
	s_movk_i32 s16, 0x4000
	s_waitcnt vmcnt(2)
	v_mov_b32_e32 v4, 0xff
	v_mov_b32_e32 v5, 0x7ff
	v_mov_b32_e32 v6, 0x100
	v_mov_b32_e32 v7, 0x800
	v_mov_b32_e32 v1, 0
	s_mov_b64 s[10:11], 0x1000
	s_mov_b64 s[12:13], 0x2000
	s_movk_i32 s17, 0x2000
	s_movk_i32 s18, 0x1ff
	v_mov_b32_e32 v8, 0x3e000000
	s_mov_b32 s19, 0x23ffff
	v_and_b32_e32 v9, 0x3f8, v3
	v_lshlrev_b32_e32 v0, 2, v9
	v_add_u32_e32 v106, 0x1000, v0
	v_add_u32_e32 v107, 0x2000, v0
	global_load_dwordx4 v[74:77], v0, s[72:73]
	global_load_dwordx4 v[78:81], v0, s[72:73] offset:16
	global_load_dwordx4 v[82:85], v0, s[26:27]
	global_load_dwordx4 v[86:89], v0, s[26:27] offset:16
	global_load_dwordx4 v[90:93], v106, s[26:27]
	global_load_dwordx4 v[94:97], v106, s[26:27] offset:16
	global_load_dwordx4 v[98:101], v107, s[26:27]
	global_load_dwordx4 v[102:105], v107, s[26:27] offset:16
	v_lshlrev_b32_e32 v68, 1, v9
	v_cmp_lt_u32_e64 s[0:1], s18, v9
	v_readfirstlane_b32 s17, v128
	s_lshl_b32 s98, s2, 9
	v_cndmask_b32_e64 v67, 1.0, v8, s[0:1]
	s_lshr_b32 s17, s17, 7
	s_lshr_b32 s8, s98, 7
	s_add_i32 s8, s8, s17
	s_cmp_lt_i32 s8, s16
	s_movk_i32 s9, 0xff
	s_cselect_b32 s9, 0x7ff, s9
	s_and_b32 s100, s8, s9
	s_cmp_lg_u32 s100, 0
	s_cselect_b32 s99, 1, 0
	s_sub_i32 s0, s8, s99
	s_lshl_b32 s0, s0, 11
	s_add_u32 s0, s4, s0
	s_addc_u32 s1, s5, 0
	global_load_dwordx4 v[46:49], v68, s[0:1]
	s_lshl_b32 s0, s8, 11
	s_add_u32 s0, s4, s0
	s_addc_u32 s1, s5, 0
	global_load_dwordx4 v[50:53], v68, s[0:1]
	s_lshl_b32 s10, s8, 11
	s_add_u32 s10, s88, s10
	s_addc_u32 s11, s89, 0
	s_cmp_lg_u32 s100, s9
	s_cselect_b32 s100, 1, 0
	s_add_i32 s0, s8, s100
	s_lshl_b32 s100, s100, 1
	s_or_b32 s99, s99, s100
	s_lshl_b32 s0, s0, 11
	s_add_u32 s0, s4, s0
	s_addc_u32 s1, s5, 0
	global_load_dwordx4 v[42:45], v68, s[0:1]
	s_add_i32 s98, s98, s14
	s_cmp_lt_i32 s98, 0x240000
	s_cbranch_scc0 .Lqkc_tail_x
	s_lshr_b32 s8, s98, 7
	s_add_i32 s8, s8, s17
	s_cmp_lt_i32 s8, s16
	s_movk_i32 s9, 0xff
	s_cselect_b32 s9, 0x7ff, s9
	s_and_b32 s100, s8, s9
	s_cmp_lg_u32 s100, 0
	s_cselect_b32 s101, 1, 0
	s_sub_i32 s0, s8, s101
	s_lshl_b32 s0, s0, 11
	s_add_u32 s0, s4, s0
	s_addc_u32 s1, s5, 0
	global_load_dwordx4 v[114:117], v68, s[0:1]
	s_lshl_b32 s0, s8, 11
	s_add_u32 s0, s4, s0
	s_addc_u32 s1, s5, 0
	global_load_dwordx4 v[118:121], v68, s[0:1]
	s_lshl_b32 s12, s8, 11
	s_add_u32 s12, s88, s12
	s_addc_u32 s13, s89, 0
	s_cmp_lg_u32 s100, s9
	s_cselect_b32 s100, 1, 0
	s_add_i32 s0, s8, s100
	s_lshl_b32 s100, s100, 1
	s_or_b32 s101, s101, s100
	s_lshl_b32 s0, s0, 11
	s_add_u32 s0, s4, s0
	s_addc_u32 s1, s5, 0
	global_load_dwordx4 v[122:125], v68, s[0:1]
	s_add_i32 s98, s98, s14
	s_waitcnt vmcnt(3)
.Lqkc_loop:
	s_waitcnt vmcnt(6)
	s_bitcmp1_b32 s99, 0
	s_cbranch_scc0 .Lqkc_off0_1
	v_lshlrev_b32_e32 v59, 16, v46
	v_and_b32_e32 v60, 0xffff0000, v46
	v_lshlrev_b32_e32 v61, 16, v47
	v_and_b32_e32 v62, 0xffff0000, v47
	v_lshlrev_b32_e32 v63, 16, v48
	v_and_b32_e32 v64, 0xffff0000, v48
	v_lshlrev_b32_e32 v65, 16, v49
	v_and_b32_e32 v66, 0xffff0000, v49
	v_fma_f32 v10, v82, v59, v74
	v_fma_f32 v11, v83, v60, v75
	v_fma_f32 v12, v84, v61, v76
	v_fma_f32 v13, v85, v62, v77
	v_fma_f32 v14, v86, v63, v78
	v_fma_f32 v15, v87, v64, v79
	v_fma_f32 v16, v88, v65, v80
	v_fma_f32 v17, v89, v66, v81
	s_branch .Lqkc_j0_1
.Lqkc_off0_1:
	v_mov_b32_e32 v10, v74
	v_mov_b32_e32 v11, v75
	v_mov_b32_e32 v12, v76
	v_mov_b32_e32 v13, v77
	v_mov_b32_e32 v14, v78
	v_mov_b32_e32 v15, v79
	v_mov_b32_e32 v16, v80
	v_mov_b32_e32 v17, v81
.Lqkc_j0_1:
	s_waitcnt vmcnt(5)
	v_lshlrev_b32_e32 v59, 16, v50
	v_and_b32_e32 v60, 0xffff0000, v50
	v_lshlrev_b32_e32 v61, 16, v51
	v_and_b32_e32 v62, 0xffff0000, v51
	v_lshlrev_b32_e32 v63, 16, v52
	v_and_b32_e32 v64, 0xffff0000, v52
	v_lshlrev_b32_e32 v65, 16, v53
	v_and_b32_e32 v66, 0xffff0000, v53
	v_fmac_f32_e32 v10, v90, v59
	v_fmac_f32_e32 v11, v91, v60
	v_fmac_f32_e32 v12, v92, v61
	v_fmac_f32_e32 v13, v93, v62
	v_fmac_f32_e32 v14, v94, v63
	v_fmac_f32_e32 v15, v95, v64
	v_fmac_f32_e32 v16, v96, v65
	v_fmac_f32_e32 v17, v97, v66
	s_waitcnt vmcnt(4)
	s_bitcmp1_b32 s99, 1
	s_cbranch_scc0 .Lqkc_off2_1
	v_lshlrev_b32_e32 v59, 16, v42
	v_and_b32_e32 v60, 0xffff0000, v42
	v_lshlrev_b32_e32 v61, 16, v43
	v_and_b32_e32 v62, 0xffff0000, v43
	v_lshlrev_b32_e32 v63, 16, v44
	v_and_b32_e32 v64, 0xffff0000, v44
	v_lshlrev_b32_e32 v65, 16, v45
	v_and_b32_e32 v66, 0xffff0000, v45
	v_fmac_f32_e32 v10, v98, v59
	v_fmac_f32_e32 v11, v99, v60
	v_fmac_f32_e32 v12, v100, v61
	v_fmac_f32_e32 v13, v101, v62
	v_fmac_f32_e32 v14, v102, v63
	v_fmac_f32_e32 v15, v103, v64
	v_fmac_f32_e32 v16, v104, v65
	v_fmac_f32_e32 v17, v105, v66
.Lqkc_off2_1:
	v_mul_f32_e32 v18, 0xbfb8aa3b, v10
	v_mul_f32_e32 v19, 0xbfb8aa3b, v11
	v_mul_f32_e32 v20, 0xbfb8aa3b, v12
	v_mul_f32_e32 v21, 0xbfb8aa3b, v13
	v_mul_f32_e32 v22, 0xbfb8aa3b, v14
	v_mul_f32_e32 v23, 0xbfb8aa3b, v15
	v_mul_f32_e32 v24, 0xbfb8aa3b, v16
	v_mul_f32_e32 v25, 0xbfb8aa3b, v17
	v_exp_f32_e32 v18, v18
	v_exp_f32_e32 v19, v19
	v_exp_f32_e32 v20, v20
	v_exp_f32_e32 v21, v21
	v_exp_f32_e32 v22, v22
	v_exp_f32_e32 v23, v23
	v_exp_f32_e32 v24, v24
	v_exp_f32_e32 v25, v25
	v_add_f32_e32 v18, 1.0, v18
	v_add_f32_e32 v19, 1.0, v19
	v_add_f32_e32 v20, 1.0, v20
	v_add_f32_e32 v21, 1.0, v21
	v_add_f32_e32 v22, 1.0, v22
	v_add_f32_e32 v23, 1.0, v23
	v_add_f32_e32 v24, 1.0, v24
	v_add_f32_e32 v25, 1.0, v25
	v_rcp_f32_e32 v18, v18
	v_rcp_f32_e32 v19, v19
	v_rcp_f32_e32 v20, v20
	v_rcp_f32_e32 v21, v21
	v_rcp_f32_e32 v22, v22
	v_rcp_f32_e32 v23, v23
	v_rcp_f32_e32 v24, v24
	v_rcp_f32_e32 v25, v25
	v_mul_f32_e32 v18, v10, v18
	v_mul_f32_e32 v19, v11, v19
	v_mul_f32_e32 v20, v12, v20
	v_mul_f32_e32 v21, v13, v21
	v_mul_f32_e32 v22, v14, v22
	v_mul_f32_e32 v23, v15, v23
	v_mul_f32_e32 v24, v16, v24
	v_mul_f32_e32 v25, v17, v25
	v_mul_f32_e32 v18, v67, v18
	v_mul_f32_e32 v19, v67, v19
	v_mul_f32_e32 v20, v67, v20
	v_mul_f32_e32 v21, v67, v21
	v_mul_f32_e32 v22, v67, v22
	v_mul_f32_e32 v23, v67, v23
	v_mul_f32_e32 v24, v67, v24
	v_mul_f32_e32 v25, v67, v25
	v_cvt_pk_bf16_f32 v10, v18, v19
	v_cvt_pk_bf16_f32 v11, v20, v21
	v_cvt_pk_bf16_f32 v12, v22, v23
	v_cvt_pk_bf16_f32 v13, v24, v25
	global_store_dwordx4 v68, v[10:13], s[10:11]
	s_cmp_lt_i32 s98, 0x240000
	s_cbranch_scc0 .Lqkc_tail_y
	s_lshr_b32 s8, s98, 7
	s_add_i32 s8, s8, s17
	s_cmp_lt_i32 s8, s16
	s_movk_i32 s9, 0xff
	s_cselect_b32 s9, 0x7ff, s9
	s_and_b32 s100, s8, s9
	s_cmp_lg_u32 s100, 0
	s_cselect_b32 s99, 1, 0
	s_sub_i32 s0, s8, s99
	s_lshl_b32 s0, s0, 11
	s_add_u32 s0, s4, s0
	s_addc_u32 s1, s5, 0
	global_load_dwordx4 v[46:49], v68, s[0:1]
	s_lshl_b32 s0, s8, 11
	s_add_u32 s0, s4, s0
	s_addc_u32 s1, s5, 0
	global_load_dwordx4 v[50:53], v68, s[0:1]
	s_lshl_b32 s10, s8, 11
	s_add_u32 s10, s88, s10
	s_addc_u32 s11, s89, 0
	s_cmp_lg_u32 s100, s9
	s_cselect_b32 s100, 1, 0
	s_add_i32 s0, s8, s100
	s_lshl_b32 s100, s100, 1
	s_or_b32 s99, s99, s100
	s_lshl_b32 s0, s0, 11
	s_add_u32 s0, s4, s0
	s_addc_u32 s1, s5, 0
	global_load_dwordx4 v[42:45], v68, s[0:1]
	s_add_i32 s98, s98, s14
	s_waitcnt vmcnt(6)
	s_bitcmp1_b32 s101, 0
	s_cbranch_scc0 .Lqkc_off0_2
	v_lshlrev_b32_e32 v59, 16, v114
	v_and_b32_e32 v60, 0xffff0000, v114
	v_lshlrev_b32_e32 v61, 16, v115
	v_and_b32_e32 v62, 0xffff0000, v115
	v_lshlrev_b32_e32 v63, 16, v116
	v_and_b32_e32 v64, 0xffff0000, v116
	v_lshlrev_b32_e32 v65, 16, v117
	v_and_b32_e32 v66, 0xffff0000, v117
	v_fma_f32 v10, v82, v59, v74
	v_fma_f32 v11, v83, v60, v75
	v_fma_f32 v12, v84, v61, v76
	v_fma_f32 v13, v85, v62, v77
	v_fma_f32 v14, v86, v63, v78
	v_fma_f32 v15, v87, v64, v79
	v_fma_f32 v16, v88, v65, v80
	v_fma_f32 v17, v89, v66, v81
	s_branch .Lqkc_j0_2

.Lqkc_j0_2:
	s_waitcnt vmcnt(5)
	v_lshlrev_b32_e32 v59, 16, v118
	v_and_b32_e32 v60, 0xffff0000, v118
	v_lshlrev_b32_e32 v61, 16, v119
	v_and_b32_e32 v62, 0xffff0000, v119
	v_lshlrev_b32_e32 v63, 16, v120
	v_and_b32_e32 v64, 0xffff0000, v120
	v_lshlrev_b32_e32 v65, 16, v121
	v_and_b32_e32 v66, 0xffff0000, v121
	v_fmac_f32_e32 v10, v90, v59
	v_fmac_f32_e32 v11, v91, v60
	v_fmac_f32_e32 v12, v92, v61
	v_fmac_f32_e32 v13, v93, v62
	v_fmac_f32_e32 v14, v94, v63
	v_fmac_f32_e32 v15, v95, v64
	v_fmac_f32_e32 v16, v96, v65
	v_fmac_f32_e32 v17, v97, v66
	s_waitcnt vmcnt(4)
	s_bitcmp1_b32 s101, 1
	s_cbranch_scc0 .Lqkc_off2_2
	v_lshlrev_b32_e32 v59, 16, v122
	v_and_b32_e32 v60, 0xffff0000, v122
	v_lshlrev_b32_e32 v61, 16, v123
	v_and_b32_e32 v62, 0xffff0000, v123
	v_lshlrev_b32_e32 v63, 16, v124
	v_and_b32_e32 v64, 0xffff0000, v124
	v_lshlrev_b32_e32 v65, 16, v125
	v_and_b32_e32 v66, 0xffff0000, v125
	v_fmac_f32_e32 v10, v98, v59
	v_fmac_f32_e32 v11, v99, v60
	v_fmac_f32_e32 v12, v100, v61
	v_fmac_f32_e32 v13, v101, v62
	v_fmac_f32_e32 v14, v102, v63
	v_fmac_f32_e32 v15, v103, v64
	v_fmac_f32_e32 v16, v104, v65
	v_fmac_f32_e32 v17, v105, v66
.Lqkc_off2_2:
	v_mul_f32_e32 v18, 0xbfb8aa3b, v10
	v_mul_f32_e32 v19, 0xbfb8aa3b, v11
	v_mul_f32_e32 v20, 0xbfb8aa3b, v12
	v_mul_f32_e32 v21, 0xbfb8aa3b, v13
	v_mul_f32_e32 v22, 0xbfb8aa3b, v14
	v_mul_f32_e32 v23, 0xbfb8aa3b, v15
	v_mul_f32_e32 v24, 0xbfb8aa3b, v16
	v_mul_f32_e32 v25, 0xbfb8aa3b, v17
	v_exp_f32_e32 v18, v18
	v_exp_f32_e32 v19, v19
	v_exp_f32_e32 v20, v20
	v_exp_f32_e32 v21, v21
	v_exp_f32_e32 v22, v22
	v_exp_f32_e32 v23, v23
	v_exp_f32_e32 v24, v24
	v_exp_f32_e32 v25, v25
	v_add_f32_e32 v18, 1.0, v18
	v_add_f32_e32 v19, 1.0, v19
	v_add_f32_e32 v20, 1.0, v20
	v_add_f32_e32 v21, 1.0, v21
	v_add_f32_e32 v22, 1.0, v22
	v_add_f32_e32 v23, 1.0, v23
	v_add_f32_e32 v24, 1.0, v24
	v_add_f32_e32 v25, 1.0, v25
	v_rcp_f32_e32 v18, v18
	v_rcp_f32_e32 v19, v19
	v_rcp_f32_e32 v20, v20
	v_rcp_f32_e32 v21, v21
	v_rcp_f32_e32 v22, v22
	v_rcp_f32_e32 v23, v23
	v_rcp_f32_e32 v24, v24
	v_rcp_f32_e32 v25, v25
	v_mul_f32_e32 v18, v10, v18
	v_mul_f32_e32 v19, v11, v19
	v_mul_f32_e32 v20, v12, v20
	v_mul_f32_e32 v21, v13, v21
	v_mul_f32_e32 v22, v14, v22
	v_mul_f32_e32 v23, v15, v23
	v_mul_f32_e32 v24, v16, v24
	v_mul_f32_e32 v25, v17, v25
	v_mul_f32_e32 v18, v67, v18
	v_mul_f32_e32 v19, v67, v19
	v_mul_f32_e32 v20, v67, v20
	v_mul_f32_e32 v21, v67, v21
	v_mul_f32_e32 v22, v67, v22
	v_mul_f32_e32 v23, v67, v23
	v_mul_f32_e32 v24, v67, v24
	v_mul_f32_e32 v25, v67, v25
	v_cvt_pk_bf16_f32 v10, v18, v19
	v_cvt_pk_bf16_f32 v11, v20, v21
	v_cvt_pk_bf16_f32 v12, v22, v23
	v_cvt_pk_bf16_f32 v13, v24, v25
	global_store_dwordx4 v68, v[10:13], s[12:13]
	s_cmp_lt_i32 s98, 0x240000
	s_cbranch_scc0 .Lqkc_tail_x
	s_lshr_b32 s8, s98, 7
	s_add_i32 s8, s8, s17
	s_cmp_lt_i32 s8, s16
	s_movk_i32 s9, 0xff
	s_cselect_b32 s9, 0x7ff, s9
	s_and_b32 s100, s8, s9
	s_cmp_lg_u32 s100, 0
	s_cselect_b32 s101, 1, 0
	s_sub_i32 s0, s8, s101
	s_lshl_b32 s0, s0, 11
	s_add_u32 s0, s4, s0
	s_addc_u32 s1, s5, 0
	global_load_dwordx4 v[114:117], v68, s[0:1]
	s_lshl_b32 s0, s8, 11
	s_add_u32 s0, s4, s0
	s_addc_u32 s1, s5, 0
	global_load_dwordx4 v[118:121], v68, s[0:1]
	s_lshl_b32 s12, s8, 11
	s_add_u32 s12, s88, s12
	s_addc_u32 s13, s89, 0
	s_cmp_lg_u32 s100, s9
	s_cselect_b32 s100, 1, 0
	s_add_i32 s0, s8, s100
	s_lshl_b32 s100, s100, 1
	s_or_b32 s101, s101, s100
	s_lshl_b32 s0, s0, 11
	s_add_u32 s0, s4, s0
	s_addc_u32 s1, s5, 0
	global_load_dwordx4 v[122:125], v68, s[0:1]
	s_add_i32 s98, s98, s14
	s_branch .Lqkc_loop
.Lqkc_tail_x:
	s_waitcnt vmcnt(0)
	s_bitcmp1_b32 s99, 0
	s_cbranch_scc0 .Lqkc_off0_3
	v_lshlrev_b32_e32 v59, 16, v46
	v_and_b32_e32 v60, 0xffff0000, v46
	v_lshlrev_b32_e32 v61, 16, v47
	v_and_b32_e32 v62, 0xffff0000, v47
	v_lshlrev_b32_e32 v63, 16, v48
	v_and_b32_e32 v64, 0xffff0000, v48
	v_lshlrev_b32_e32 v65, 16, v49
	v_and_b32_e32 v66, 0xffff0000, v49
	v_fma_f32 v10, v82, v59, v74
	v_fma_f32 v11, v83, v60, v75
	v_fma_f32 v12, v84, v61, v76
	v_fma_f32 v13, v85, v62, v77
	v_fma_f32 v14, v86, v63, v78
	v_fma_f32 v15, v87, v64, v79
	v_fma_f32 v16, v88, v65, v80
	v_fma_f32 v17, v89, v66, v81
	s_branch .Lqkc_j0_3

.Lqkc_j0_3:
	v_lshlrev_b32_e32 v59, 16, v50
	v_and_b32_e32 v60, 0xffff0000, v50
	v_lshlrev_b32_e32 v61, 16, v51
	v_and_b32_e32 v62, 0xffff0000, v51
	v_lshlrev_b32_e32 v63, 16, v52
	v_and_b32_e32 v64, 0xffff0000, v52
	v_lshlrev_b32_e32 v65, 16, v53
	v_and_b32_e32 v66, 0xffff0000, v53
	v_fmac_f32_e32 v10, v90, v59
	v_fmac_f32_e32 v11, v91, v60
	v_fmac_f32_e32 v12, v92, v61
	v_fmac_f32_e32 v13, v93, v62
	v_fmac_f32_e32 v14, v94, v63
	v_fmac_f32_e32 v15, v95, v64
	v_fmac_f32_e32 v16, v96, v65
	v_fmac_f32_e32 v17, v97, v66
	s_bitcmp1_b32 s99, 1
	s_cbranch_scc0 .Lqkc_off2_3
	v_lshlrev_b32_e32 v59, 16, v42
	v_and_b32_e32 v60, 0xffff0000, v42
	v_lshlrev_b32_e32 v61, 16, v43
	v_and_b32_e32 v62, 0xffff0000, v43
	v_lshlrev_b32_e32 v63, 16, v44
	v_and_b32_e32 v64, 0xffff0000, v44
	v_lshlrev_b32_e32 v65, 16, v45
	v_and_b32_e32 v66, 0xffff0000, v45
	v_fmac_f32_e32 v10, v98, v59
	v_fmac_f32_e32 v11, v99, v60
	v_fmac_f32_e32 v12, v100, v61
	v_fmac_f32_e32 v13, v101, v62
	v_fmac_f32_e32 v14, v102, v63
	v_fmac_f32_e32 v15, v103, v64
	v_fmac_f32_e32 v16, v104, v65
	v_fmac_f32_e32 v17, v105, v66
.Lqkc_off2_3:
	v_mul_f32_e32 v18, 0xbfb8aa3b, v10
	v_mul_f32_e32 v19, 0xbfb8aa3b, v11
	v_mul_f32_e32 v20, 0xbfb8aa3b, v12
	v_mul_f32_e32 v21, 0xbfb8aa3b, v13
	v_mul_f32_e32 v22, 0xbfb8aa3b, v14
	v_mul_f32_e32 v23, 0xbfb8aa3b, v15
	v_mul_f32_e32 v24, 0xbfb8aa3b, v16
	v_mul_f32_e32 v25, 0xbfb8aa3b, v17
	v_exp_f32_e32 v18, v18
	v_exp_f32_e32 v19, v19
	v_exp_f32_e32 v20, v20
	v_exp_f32_e32 v21, v21
	v_exp_f32_e32 v22, v22
	v_exp_f32_e32 v23, v23
	v_exp_f32_e32 v24, v24
	v_exp_f32_e32 v25, v25
	v_add_f32_e32 v18, 1.0, v18
	v_add_f32_e32 v19, 1.0, v19
	v_add_f32_e32 v20, 1.0, v20
	v_add_f32_e32 v21, 1.0, v21
	v_add_f32_e32 v22, 1.0, v22
	v_add_f32_e32 v23, 1.0, v23
	v_add_f32_e32 v24, 1.0, v24
	v_add_f32_e32 v25, 1.0, v25
	v_rcp_f32_e32 v18, v18
	v_rcp_f32_e32 v19, v19
	v_rcp_f32_e32 v20, v20
	v_rcp_f32_e32 v21, v21
	v_rcp_f32_e32 v22, v22
	v_rcp_f32_e32 v23, v23
	v_rcp_f32_e32 v24, v24
	v_rcp_f32_e32 v25, v25
	v_mul_f32_e32 v18, v10, v18
	v_mul_f32_e32 v19, v11, v19
	v_mul_f32_e32 v20, v12, v20
	v_mul_f32_e32 v21, v13, v21
	v_mul_f32_e32 v22, v14, v22
	v_mul_f32_e32 v23, v15, v23
	v_mul_f32_e32 v24, v16, v24
	v_mul_f32_e32 v25, v17, v25
	v_mul_f32_e32 v18, v67, v18
	v_mul_f32_e32 v19, v67, v19
	v_mul_f32_e32 v20, v67, v20
	v_mul_f32_e32 v21, v67, v21
	v_mul_f32_e32 v22, v67, v22
	v_mul_f32_e32 v23, v67, v23
	v_mul_f32_e32 v24, v67, v24
	v_mul_f32_e32 v25, v67, v25
	v_cvt_pk_bf16_f32 v10, v18, v19
	v_cvt_pk_bf16_f32 v11, v20, v21
	v_cvt_pk_bf16_f32 v12, v22, v23
	v_cvt_pk_bf16_f32 v13, v24, v25
	global_store_dwordx4 v68, v[10:13], s[10:11]
	s_branch .LBB0_1611
.Lqkc_tail_y:
	s_waitcnt vmcnt(0)
	s_bitcmp1_b32 s101, 0
	s_cbranch_scc0 .Lqkc_off0_4
	v_lshlrev_b32_e32 v59, 16, v114
	v_and_b32_e32 v60, 0xffff0000, v114
	v_lshlrev_b32_e32 v61, 16, v115
	v_and_b32_e32 v62, 0xffff0000, v115
	v_lshlrev_b32_e32 v63, 16, v116
	v_and_b32_e32 v64, 0xffff0000, v116
	v_lshlrev_b32_e32 v65, 16, v117
	v_and_b32_e32 v66, 0xffff0000, v117
	v_fma_f32 v10, v82, v59, v74
	v_fma_f32 v11, v83, v60, v75
	v_fma_f32 v12, v84, v61, v76
	v_fma_f32 v13, v85, v62, v77
	v_fma_f32 v14, v86, v63, v78
	v_fma_f32 v15, v87, v64, v79
	v_fma_f32 v16, v88, v65, v80
	v_fma_f32 v17, v89, v66, v81
	s_branch .Lqkc_j0_4

.Lqkc_j0_4:
	v_lshlrev_b32_e32 v59, 16, v118
	v_and_b32_e32 v60, 0xffff0000, v118
	v_lshlrev_b32_e32 v61, 16, v119
	v_and_b32_e32 v62, 0xffff0000, v119
	v_lshlrev_b32_e32 v63, 16, v120
	v_and_b32_e32 v64, 0xffff0000, v120
	v_lshlrev_b32_e32 v65, 16, v121
	v_and_b32_e32 v66, 0xffff0000, v121
	v_fmac_f32_e32 v10, v90, v59
	v_fmac_f32_e32 v11, v91, v60
	v_fmac_f32_e32 v12, v92, v61
	v_fmac_f32_e32 v13, v93, v62
	v_fmac_f32_e32 v14, v94, v63
	v_fmac_f32_e32 v15, v95, v64
	v_fmac_f32_e32 v16, v96, v65
	v_fmac_f32_e32 v17, v97, v66
	s_bitcmp1_b32 s101, 1
	s_cbranch_scc0 .Lqkc_off2_4
	v_lshlrev_b32_e32 v59, 16, v122
	v_and_b32_e32 v60, 0xffff0000, v122
	v_lshlrev_b32_e32 v61, 16, v123
	v_and_b32_e32 v62, 0xffff0000, v123
	v_lshlrev_b32_e32 v63, 16, v124
	v_and_b32_e32 v64, 0xffff0000, v124
	v_lshlrev_b32_e32 v65, 16, v125
	v_and_b32_e32 v66, 0xffff0000, v125
	v_fmac_f32_e32 v10, v98, v59
	v_fmac_f32_e32 v11, v99, v60
	v_fmac_f32_e32 v12, v100, v61
	v_fmac_f32_e32 v13, v101, v62
	v_fmac_f32_e32 v14, v102, v63
	v_fmac_f32_e32 v15, v103, v64
	v_fmac_f32_e32 v16, v104, v65
	v_fmac_f32_e32 v17, v105, v66
.Lqkc_off2_4:
	v_mul_f32_e32 v18, 0xbfb8aa3b, v10
	v_mul_f32_e32 v19, 0xbfb8aa3b, v11
	v_mul_f32_e32 v20, 0xbfb8aa3b, v12
	v_mul_f32_e32 v21, 0xbfb8aa3b, v13
	v_mul_f32_e32 v22, 0xbfb8aa3b, v14
	v_mul_f32_e32 v23, 0xbfb8aa3b, v15
	v_mul_f32_e32 v24, 0xbfb8aa3b, v16
	v_mul_f32_e32 v25, 0xbfb8aa3b, v17
	v_exp_f32_e32 v18, v18
	v_exp_f32_e32 v19, v19
	v_exp_f32_e32 v20, v20
	v_exp_f32_e32 v21, v21
	v_exp_f32_e32 v22, v22
	v_exp_f32_e32 v23, v23
	v_exp_f32_e32 v24, v24
	v_exp_f32_e32 v25, v25
	v_add_f32_e32 v18, 1.0, v18
	v_add_f32_e32 v19, 1.0, v19
	v_add_f32_e32 v20, 1.0, v20
	v_add_f32_e32 v21, 1.0, v21
	v_add_f32_e32 v22, 1.0, v22
	v_add_f32_e32 v23, 1.0, v23
	v_add_f32_e32 v24, 1.0, v24
	v_add_f32_e32 v25, 1.0, v25
	v_rcp_f32_e32 v18, v18
	v_rcp_f32_e32 v19, v19
	v_rcp_f32_e32 v20, v20
	v_rcp_f32_e32 v21, v21
	v_rcp_f32_e32 v22, v22
	v_rcp_f32_e32 v23, v23
	v_rcp_f32_e32 v24, v24
	v_rcp_f32_e32 v25, v25
	v_mul_f32_e32 v18, v10, v18
	v_mul_f32_e32 v19, v11, v19
	v_mul_f32_e32 v20, v12, v20
	v_mul_f32_e32 v21, v13, v21
	v_mul_f32_e32 v22, v14, v22
	v_mul_f32_e32 v23, v15, v23
	v_mul_f32_e32 v24, v16, v24
	v_mul_f32_e32 v25, v17, v25
	v_mul_f32_e32 v18, v67, v18
	v_mul_f32_e32 v19, v67, v19
	v_mul_f32_e32 v20, v67, v20
	v_mul_f32_e32 v21, v67, v21
	v_mul_f32_e32 v22, v67, v22
	v_mul_f32_e32 v23, v67, v23
	v_mul_f32_e32 v24, v67, v24
	v_mul_f32_e32 v25, v67, v25
	v_cvt_pk_bf16_f32 v10, v18, v19
	v_cvt_pk_bf16_f32 v11, v20, v21
	v_cvt_pk_bf16_f32 v12, v22, v23
	v_cvt_pk_bf16_f32 v13, v24, v25
	global_store_dwordx4 v68, v[10:13], s[12:13]
